# K/V prefetch loads spread over steps 1/3/5 of the iteration instead of one VMEM burst right behind the tile barrier
# baseline (speedup 1.0000x reference)
; #define LAS __attribute__((address_space(3)))
; __device__ __forceinline__ float swap_max(float m) { auto rr = __builtin_amdgcn_permlane32_swap(__float_as_uint(m), __float_as_uint(m), false, false); return fmaxf(__uint_as_float(rr[0]), __uint_as_float(rr[1])); }
; #define MLA_PACK(P, b) (u32x4){cvt_pk_bf16(P[b], P[b + 1]), cvt_pk_bf16(P[b + 2], P[b + 3]), cvt_pk_bf16(P[b + 4], P[b + 5]), cvt_pk_bf16(P[b + 6], P[b + 7])}
; __device__ __forceinline__ void softmax_blk(f32x16& p0, f32x16& p1, f32x16& o0, f32x16& o1, float& mhat, float& lrun, u32x4 (&pf)[4], bool first) {
;     float r0 = max2_(p0[0], p0[1]), r1 = max2_(p1[0], p1[1]);
; #pragma unroll
;     for (int e = 2; e < 16; ++e) { r0 = max2_(r0, p0[e]); r1 = max2_(r1, p1[e]); }
;     const float rm = swap_max(max2_(r0, r1));
;     if (first || __any(rm - mhat > THR)) {
;         const float mn = first ? rm : fmaxf(rm, mhat); const float f = first ? 0.f : __builtin_amdgcn_exp2f(mhat - mn); mhat = mn; lrun *= f;
; #pragma unroll
;         for (int e = 0; e < 16; ++e) { o0[e] *= f; o1[e] *= f; }
;     }
;     float s0 = 0.f, s1 = 0.f;
; #pragma unroll
;     for (int e = 0; e < 16; ++e) { p0[e] = __builtin_amdgcn_exp2f(p0[e] - mhat); p1[e] = __builtin_amdgcn_exp2f(p1[e] - mhat); s0 += p0[e]; s1 += p1[e]; }
;     lrun += s0 + s1;
;     pf[0] = MLA_PACK(p0, 0); pf[1] = MLA_PACK(p0, 8); pf[2] = MLA_PACK(p1, 0); pf[3] = MLA_PACK(p1, 8);
; }
; __device__ __forceinline__ void attn_unit(const bf16_t* Qh, const bf16_t* Kh, const bf16_t* Vh, bf16_t* Oh  , int S, int qb, LAS unsigned char* lds, int tid) {
;     ...
;         ka = GLD(u32x4, Kg + (size_t)tn * 768 + kc0); kb = GLD(u32x4, Kg + (size_t)tn * 768 + kc1); va = GLD(u32x4, Vg + (size_t)tn * 512 + tid);
;         u32x4 pf[4];
;         {
;             f32x16 p0 = {}, p1 = {};
; #pragma unroll
;             for (int s = 0; s < 6; ++s) {
;                 const bf16x8 a0 = *(const LAS bf16x8*)(lds + cur + kfo + s * 32), a1 = *(const LAS bf16x8*)(lds + cur + kfo + 32 * KPITCH + s * 32);
;                 const bf16x8 q = *(const LAS bf16x8*)(ql + s * 1024);
;                 p0 = __builtin_amdgcn_mfma_f32_32x32x16_bf16(a0, q, p0, 0, 0, 0); p1 = __builtin_amdgcn_mfma_f32_32x32x16_bf16(a1, q, p1, 0, 0, 0);
;             }
;             softmax_blk(p0, p1, oa0, oa1, ma, la, pf, t == 0);
;             pv_blk(pf, oa0, oa1, lds + cur + vb);
.Lmla_top:
	ds_read_b64_tr_b16 v[128:129], v158 offset:13312
	ds_read_b64_tr_b16 v[130:131], v158 offset:13824
	ds_read_b64_tr_b16 v[142:143], v158 offset:17408
	ds_read_b64_tr_b16 v[144:145], v158 offset:17920
	ds_read_b64_tr_b16 v[176:177], v158 offset:14336
	ds_read_b64_tr_b16 v[178:179], v158 offset:14848
	ds_read_b64_tr_b16 v[180:181], v158 offset:18432
	ds_read_b64_tr_b16 v[182:183], v158 offset:18944
	s_waitcnt lgkmcnt(4)
	v_mfma_f32_32x32x16_bf16 v[16:31], v[128:131], v[64:67], v[16:31]
	v_mfma_f32_32x32x16_bf16 v[0:15], v[142:145], v[64:67], v[0:15]
	ds_read_b64_tr_b16 v[128:129], v158 offset:15360
	ds_read_b64_tr_b16 v[130:131], v158 offset:15872
	ds_read_b64_tr_b16 v[142:143], v158 offset:19456
	ds_read_b64_tr_b16 v[144:145], v158 offset:19968
	v_max3_f32 v248, v96, v97, v98
	v_max3_f32 v249, v112, v113, v114
	v_max3_f32 v248, v248, v99, v100
	v_max3_f32 v249, v249, v115, v116
	v_max3_f32 v248, v248, v101, v102
	v_max3_f32 v249, v249, v117, v118
	v_max3_f32 v248, v248, v103, v104
	v_max3_f32 v249, v249, v119, v120
	v_max3_f32 v248, v248, v105, v106
	v_max3_f32 v249, v249, v121, v122
	v_max3_f32 v248, v248, v107, v108
	v_max3_f32 v249, v249, v123, v124
	v_max3_f32 v248, v248, v109, v110
	v_max3_f32 v249, v249, v125, v126
	s_waitcnt lgkmcnt(4)
	v_mfma_f32_32x32x16_bf16 v[16:31], v[176:179], v[68:71], v[16:31]
	v_mfma_f32_32x32x16_bf16 v[0:15], v[180:183], v[68:71], v[0:15]
	ds_read_b64_tr_b16 v[176:177], v158 offset:16384
	ds_read_b64_tr_b16 v[178:179], v158 offset:16896
	ds_read_b64_tr_b16 v[180:181], v158 offset:20480
	ds_read_b64_tr_b16 v[182:183], v158 offset:20992
	global_load_dwordx4 v[218:221], v171, s[26:27]
	v_max3_f32 v248, v248, v111, v127
	v_max_f32_e32 v248, v248, v249
	v_mov_b32_e32 v251, v248
	s_nop 1
	v_permlane32_swap_b32_e32 v248, v251
	v_max_f32_e32 v167, v248, v251
	v_cmp_lt_f32_e32 vcc, s72, v167
	s_cbranch_vccnz .Lmla_rescBo
.Lmla_rescBo_back:
	v_exp_f32_e32 v96, v96
	v_exp_f32_e32 v97, v97
	v_exp_f32_e32 v98, v98
	s_waitcnt lgkmcnt(4)
	v_mfma_f32_32x32x16_bf16 v[16:31], v[128:131], v[72:75], v[16:31]
	v_mfma_f32_32x32x16_bf16 v[0:15], v[142:145], v[72:75], v[0:15]
	ds_read_b128 v[128:131], v155 offset:21504
	ds_read_b128 v[142:145], v155 offset:28160
	ds_read_b128 v[162:165], v135 offset:43008
	v_exp_f32_e32 v99, v99
	v_exp_f32_e32 v100, v100
	v_exp_f32_e32 v101, v101
	v_exp_f32_e32 v102, v102
	v_exp_f32_e32 v103, v103
	v_add_f32_e32 v166, v96, v97
	v_add_f32_e32 v141, v141, v98
	v_add_f32_e32 v166, v166, v99
	s_waitcnt lgkmcnt(3)
	v_mfma_f32_32x32x16_bf16 v[16:31], v[176:179], v[76:79], v[16:31]
	v_mfma_f32_32x32x16_bf16 v[0:15], v[180:183], v[76:79], v[0:15]
	ds_read_b128 v[176:179], v155 offset:21536
	ds_read_b128 v[180:183], v155 offset:28192
	ds_read_b128 v[186:189], v135 offset:44032
	s_cmp_eq_u64 s[36:37], 0
	s_cbranch_scc1 .Lmla_nok1Ao
	global_load_dwordx4 v[222:225], v184, s[26:27]
.Lmla_nok1Ao:
	v_cvt_pk_bf16_f32 v96, v96, v97
	v_cvt_pk_bf16_f32 v97, v98, v99
	v_exp_f32_e32 v104, v104
	v_exp_f32_e32 v105, v105
	v_exp_f32_e32 v106, v106
	v_exp_f32_e32 v107, v107
	v_add_f32_e32 v141, v141, v100
	v_add_f32_e32 v166, v166, v101
	v_add_f32_e32 v141, v141, v102
	s_waitcnt lgkmcnt(3)
	v_mfma_f32_32x32x16_bf16 v[64:79], v[128:131], v[162:165], v[232:247]
	v_mfma_f32_32x32x16_bf16 v[80:95], v[142:145], v[162:165], v[232:247]
	ds_read_b128 v[128:131], v155 offset:21568
	ds_read_b128 v[142:145], v155 offset:28224
	ds_read_b128 v[162:165], v135 offset:45056
	v_add_f32_e32 v166, v166, v103
	v_cvt_pk_bf16_f32 v98, v100, v101
	v_cvt_pk_bf16_f32 v99, v102, v103
	v_exp_f32_e32 v108, v108
	v_exp_f32_e32 v109, v109
	v_exp_f32_e32 v110, v110
	v_exp_f32_e32 v111, v111
	v_add_f32_e32 v141, v141, v104
	v_add_f32_e32 v166, v166, v105
	s_waitcnt lgkmcnt(3)
	v_mfma_f32_32x32x16_bf16 v[64:79], v[176:179], v[186:189], v[64:79]
	v_mfma_f32_32x32x16_bf16 v[80:95], v[180:183], v[186:189], v[80:95]
	ds_read_b128 v[176:179], v155 offset:21600
	ds_read_b128 v[180:183], v155 offset:28256
	ds_read_b128 v[186:189], v135 offset:46080
	global_load_dwordx4 v[226:229], v146, s[100:101]
	s_add_u32 s26, s26, 0x3000
	s_addc_u32 s27, s27, 0
	s_add_u32 s100, s100, 0x2000
	s_addc_u32 s101, s101, 0
	v_add_f32_e32 v141, v141, v106
	v_add_f32_e32 v166, v166, v107
	v_cvt_pk_bf16_f32 v100, v104, v105
	v_cvt_pk_bf16_f32 v101, v106, v107
	v_exp_f32_e32 v112, v112
	v_exp_f32_e32 v113, v113
	v_exp_f32_e32 v114, v114
	v_exp_f32_e32 v115, v115
	v_add_f32_e32 v141, v141, v108
	v_add_f32_e32 v166, v166, v109
	s_waitcnt lgkmcnt(3)
	v_mfma_f32_32x32x16_bf16 v[64:79], v[128:131], v[162:165], v[64:79]
	v_mfma_f32_32x32x16_bf16 v[80:95], v[142:145], v[162:165], v[80:95]
	ds_read_b128 v[128:131], v155 offset:21632
	ds_read_b128 v[142:145], v155 offset:28288
	ds_read_b128 v[162:165], v135 offset:47104
	v_add_f32_e32 v141, v141, v110
	v_add_f32_e32 v166, v166, v111
	v_cvt_pk_bf16_f32 v102, v108, v109
	v_cvt_pk_bf16_f32 v103, v110, v111
	v_exp_f32_e32 v116, v116
	v_exp_f32_e32 v117, v117
	v_exp_f32_e32 v118, v118
	v_exp_f32_e32 v119, v119
	v_add_f32_e32 v141, v141, v112
	s_waitcnt lgkmcnt(3)
	v_mfma_f32_32x32x16_bf16 v[64:79], v[176:179], v[186:189], v[64:79]
	v_mfma_f32_32x32x16_bf16 v[80:95], v[180:183], v[186:189], v[80:95]
	ds_read_b128 v[176:179], v155 offset:21664
	ds_read_b128 v[180:183], v155 offset:28320
	ds_read_b128 v[186:189], v135 offset:48128
	v_add_f32_e32 v166, v166, v113
	v_add_f32_e32 v141, v141, v114
	v_add_f32_e32 v166, v166, v115
	v_cvt_pk_bf16_f32 v104, v112, v113
	v_cvt_pk_bf16_f32 v105, v114, v115
	v_exp_f32_e32 v120, v120
	v_exp_f32_e32 v121, v121
	v_exp_f32_e32 v122, v122
	v_exp_f32_e32 v123, v123
	v_add_f32_e32 v141, v141, v116
	s_waitcnt lgkmcnt(3)
; #define LAS __attribute__((address_space(3)))
; __device__ __forceinline__ void softmax_blk(f32x16& p0, f32x16& p1, f32x16& o0, f32x16& o1, float& mhat, float& lrun, u32x4 (&pf)[4], bool first) {
;     float r0 = max2_(p0[0], p0[1]), r1 = max2_(p1[0], p1[1]);
; #pragma unroll
;     for (int e = 2; e < 16; ++e) { r0 = max2_(r0, p0[e]); r1 = max2_(r1, p1[e]); }
;     const float rm = swap_max(max2_(r0, r1));
;     if (first || __any(rm - mhat > THR)) {
;         const float mn = first ? rm : fmaxf(rm, mhat); const float f = first ? 0.f : __builtin_amdgcn_exp2f(mhat - mn); mhat = mn; lrun *= f;
; #pragma unroll
;         for (int e = 0; e < 16; ++e) { o0[e] *= f; o1[e] *= f; }
;     }
;     float s0 = 0.f, s1 = 0.f;
; #pragma unroll
;     for (int e = 0; e < 16; ++e) { p0[e] = __builtin_amdgcn_exp2f(p0[e] - mhat); p1[e] = __builtin_amdgcn_exp2f(p1[e] - mhat); s0 += p0[e]; s1 += p1[e]; }
;     lrun += s0 + s1;
;     pf[0] = MLA_PACK(p0, 0); pf[1] = MLA_PACK(p0, 8); pf[2] = MLA_PACK(p1, 0); pf[3] = MLA_PACK(p1, 8);
; }
; __device__ __forceinline__ void pv_blk(const u32x4 (&pf)[4], f32x16& o0, f32x16& o1, LAS const unsigned char* vbase) {
; #pragma unroll
;     for (int ks = 0; ks < 4; ++ks) {
;         const bf16x8 p = __builtin_bit_cast(bf16x8, pf[ks]);
;         { const s16x4 lo = vtr(vbase + ks * 1024), hh = vtr(vbase + ks * 1024 + 512); const bf16x8 vf = {lo[0], lo[1], lo[2], lo[3], hh[0], hh[1], hh[2], hh[3]};
;           o0 = __builtin_amdgcn_mfma_f32_32x32x16_bf16(vf, p, o0, 0, 0, 0); }
;         { const s16x4 lo = vtr(vbase + 4096 + ks * 1024), hh = vtr(vbase + 4096 + ks * 1024 + 512); const bf16x8 vf = {lo[0], lo[1], lo[2], lo[3], hh[0], hh[1], hh[2], hh[3]};
;           o1 = __builtin_amdgcn_mfma_f32_32x32x16_bf16(vf, p, o1, 0, 0, 0); }
;     }
; }
; __device__ __forceinline__ void attn_unit(const bf16_t* Qh, const bf16_t* Kh, const bf16_t* Vh, bf16_t* Oh  , int S, int qb, LAS unsigned char* lds, int tid) {
;     ...
;         ka = GLD(u32x4, Kg + (size_t)tn * 768 + kc0); kb = GLD(u32x4, Kg + (size_t)tn * 768 + kc1); va = GLD(u32x4, Vg + (size_t)tn * 512 + tid);
;         u32x4 pf[4];
;         {
;             f32x16 p0 = {}, p1 = {};
; #pragma unroll
;             for (int s = 0; s < 6; ++s) {
;                 const bf16x8 a0 = *(const LAS bf16x8*)(lds + cur + kfo + s * 32), a1 = *(const LAS bf16x8*)(lds + cur + kfo + 32 * KPITCH + s * 32);
	v_mfma_f32_32x32x16_bf16 v[64:79], v[128:131], v[162:165], v[64:79]
	v_mfma_f32_32x32x16_bf16 v[80:95], v[142:145], v[162:165], v[80:95]
	ds_read_b64_tr_b16 v[128:129], v158 offset:13312
	ds_read_b64_tr_b16 v[130:131], v158 offset:13824
	ds_read_b64_tr_b16 v[142:143], v158 offset:17408
	ds_read_b64_tr_b16 v[144:145], v158 offset:17920
	v_add_f32_e32 v166, v166, v117
	v_add_f32_e32 v141, v141, v118
	v_add_f32_e32 v166, v166, v119
	v_cvt_pk_bf16_f32 v106, v116, v117
	v_cvt_pk_bf16_f32 v107, v118, v119
	v_exp_f32_e32 v124, v124
	v_exp_f32_e32 v125, v125
	v_exp_f32_e32 v126, v126
	v_exp_f32_e32 v127, v127
	s_waitcnt lgkmcnt(4)
	v_mfma_f32_32x32x16_bf16 v[64:79], v[176:179], v[186:189], v[64:79]
	v_mfma_f32_32x32x16_bf16 v[80:95], v[180:183], v[186:189], v[80:95]
	ds_read_b64_tr_b16 v[176:177], v158 offset:14336
	ds_read_b64_tr_b16 v[178:179], v158 offset:14848
	ds_read_b64_tr_b16 v[180:181], v158 offset:18432
	ds_read_b64_tr_b16 v[182:183], v158 offset:18944
	v_add_f32_e32 v141, v141, v120
	v_add_f32_e32 v166, v166, v121
	v_add_f32_e32 v141, v141, v122
	v_add_f32_e32 v166, v166, v123
	v_cvt_pk_bf16_f32 v108, v120, v121
	v_cvt_pk_bf16_f32 v109, v122, v123
	v_add_f32_e32 v141, v141, v124
	v_add_f32_e32 v166, v166, v125
	v_add_f32_e32 v141, v141, v126
	v_add_f32_e32 v166, v166, v127
	v_cvt_pk_bf16_f32 v110, v124, v125
	v_cvt_pk_bf16_f32 v111, v126, v127
	v_add_f32_e32 v141, v141, v166
	s_waitcnt lgkmcnt(4)
	v_mfma_f32_32x32x16_bf16 v[48:63], v[128:131], v[96:99], v[48:63]
	v_mfma_f32_32x32x16_bf16 v[32:47], v[142:145], v[96:99], v[32:47]
	ds_read_b64_tr_b16 v[128:129], v158 offset:15360
	ds_read_b64_tr_b16 v[130:131], v158 offset:15872
	ds_read_b64_tr_b16 v[142:143], v158 offset:19456
	ds_read_b64_tr_b16 v[144:145], v158 offset:19968
	v_max3_f32 v248, v64, v65, v66
	v_max3_f32 v249, v80, v81, v82
	v_max3_f32 v248, v248, v67, v68
	v_max3_f32 v249, v249, v83, v84
	v_max3_f32 v248, v248, v69, v70
	v_max3_f32 v249, v249, v85, v86
	v_max3_f32 v248, v248, v71, v72
	v_max3_f32 v249, v249, v87, v88
	v_max3_f32 v248, v248, v73, v74
	v_max3_f32 v249, v249, v89, v90
	v_max3_f32 v248, v248, v75, v76
	v_max3_f32 v249, v249, v91, v92
	v_max3_f32 v248, v248, v77, v78
	v_max3_f32 v249, v249, v93, v94
	s_waitcnt lgkmcnt(4)
	v_mfma_f32_32x32x16_bf16 v[48:63], v[176:179], v[100:103], v[48:63]
	v_mfma_f32_32x32x16_bf16 v[32:47], v[180:183], v[100:103], v[32:47]
	ds_read_b64_tr_b16 v[176:177], v158 offset:16384
	ds_read_b64_tr_b16 v[178:179], v158 offset:16896
	ds_read_b64_tr_b16 v[180:181], v158 offset:20480
	ds_read_b64_tr_b16 v[182:183], v158 offset:20992
	v_max3_f32 v248, v248, v79, v95
	v_max_f32_e32 v248, v248, v249
	v_mov_b32_e32 v251, v248
	s_nop 1
	v_permlane32_swap_b32_e32 v248, v251
	v_max_f32_e32 v167, v248, v251
	v_cmp_lt_f32_e32 vcc, s72, v167
	s_cbranch_vccnz .Lmla_rescAo
.Lmla_rescAo_back:
	v_exp_f32_e32 v64, v64
	v_exp_f32_e32 v65, v65
	v_exp_f32_e32 v66, v66
	s_waitcnt lgkmcnt(4)
	v_mfma_f32_32x32x16_bf16 v[48:63], v[128:131], v[104:107], v[48:63]
	v_mfma_f32_32x32x16_bf16 v[32:47], v[142:145], v[104:107], v[32:47]
	ds_read_b128 v[128:131], v155 offset:21504
	ds_read_b128 v[142:145], v155 offset:28160
	ds_read_b128 v[162:165], v135 offset:49152
	v_exp_f32_e32 v67, v67
	v_exp_f32_e32 v68, v68
	v_exp_f32_e32 v69, v69
	v_exp_f32_e32 v70, v70
	v_exp_f32_e32 v71, v71
	v_add_f32_e32 v166, v64, v65
	v_add_f32_e32 v140, v140, v66
	v_add_f32_e32 v166, v166, v67
	s_waitcnt lgkmcnt(3)
	v_mfma_f32_32x32x16_bf16 v[48:63], v[176:179], v[108:111], v[48:63]
	v_mfma_f32_32x32x16_bf16 v[32:47], v[180:183], v[108:111], v[32:47]
	ds_read_b128 v[176:179], v155 offset:21536
	ds_read_b128 v[180:183], v155 offset:28192
	ds_read_b128 v[186:189], v135 offset:50176
	v_cvt_pk_bf16_f32 v64, v64, v65
	v_cvt_pk_bf16_f32 v65, v66, v67
	v_exp_f32_e32 v72, v72
	v_exp_f32_e32 v73, v73
	v_exp_f32_e32 v74, v74
	v_exp_f32_e32 v75, v75
	v_add_f32_e32 v140, v140, v68
	v_add_f32_e32 v166, v166, v69
	v_add_f32_e32 v140, v140, v70
	s_waitcnt lgkmcnt(3)
	v_mfma_f32_32x32x16_bf16 v[96:111], v[128:131], v[162:165], v[190:205]
	v_mfma_f32_32x32x16_bf16 v[112:127], v[142:145], v[162:165], v[190:205]
	ds_read_b128 v[128:131], v155 offset:21568
	ds_read_b128 v[142:145], v155 offset:28224
	ds_read_b128 v[162:165], v135 offset:51200
	v_add_f32_e32 v166, v166, v71
	v_cvt_pk_bf16_f32 v66, v68, v69
	v_cvt_pk_bf16_f32 v67, v70, v71
	v_exp_f32_e32 v76, v76
	v_exp_f32_e32 v77, v77
	v_exp_f32_e32 v78, v78
	v_exp_f32_e32 v79, v79
	v_add_f32_e32 v140, v140, v72
	v_add_f32_e32 v166, v166, v73
	s_waitcnt lgkmcnt(3)
	v_mfma_f32_32x32x16_bf16 v[96:111], v[176:179], v[186:189], v[96:111]
	v_mfma_f32_32x32x16_bf16 v[112:127], v[180:183], v[186:189], v[112:127]
	ds_read_b128 v[176:179], v155 offset:21600
	ds_read_b128 v[180:183], v155 offset:28256
	ds_read_b128 v[186:189], v135 offset:52224
	v_add_f32_e32 v140, v140, v74
	v_add_f32_e32 v166, v166, v75
	v_cvt_pk_bf16_f32 v68, v72, v73
	v_cvt_pk_bf16_f32 v69, v74, v75
	v_exp_f32_e32 v80, v80
	v_exp_f32_e32 v81, v81
	v_exp_f32_e32 v82, v82
	v_exp_f32_e32 v83, v83
	v_add_f32_e32 v140, v140, v76
	v_add_f32_e32 v166, v166, v77
	s_waitcnt lgkmcnt(3)
	v_mfma_f32_32x32x16_bf16 v[96:111], v[128:131], v[162:165], v[96:111]
	v_mfma_f32_32x32x16_bf16 v[112:127], v[142:145], v[162:165], v[112:127]
	ds_read_b128 v[128:131], v155 offset:21632
	ds_read_b128 v[142:145], v155 offset:28288
	ds_read_b128 v[162:165], v135 offset:53248
	v_add_f32_e32 v140, v140, v78
	v_add_f32_e32 v166, v166, v79
	v_cvt_pk_bf16_f32 v70, v76, v77
	v_cvt_pk_bf16_f32 v71, v78, v79
	v_exp_f32_e32 v84, v84
	v_exp_f32_e32 v85, v85
	v_exp_f32_e32 v86, v86
	v_exp_f32_e32 v87, v87
	v_add_f32_e32 v140, v140, v80
	s_waitcnt lgkmcnt(3)
; __device__ __forceinline__ void softmax_blk(f32x16& p0, f32x16& p1, f32x16& o0, f32x16& o1, float& mhat, float& lrun, u32x4 (&pf)[4], bool first) {
;     float r0 = max2_(p0[0], p0[1]), r1 = max2_(p1[0], p1[1]);
; #pragma unroll
;     for (int e = 2; e < 16; ++e) { r0 = max2_(r0, p0[e]); r1 = max2_(r1, p1[e]); }
;     const float rm = swap_max(max2_(r0, r1));
;     if (first || __any(rm - mhat > THR)) {
; __device__ __forceinline__ void attn_unit(const bf16_t* Qh, const bf16_t* Kh, const bf16_t* Vh, bf16_t* Oh  , int S, int qb, LAS unsigned char* lds, int tid) {
;     ...
;     for (int t = 0; t < NT; ++t) {
;         const unsigned cur = (unsigned)(t & 1) * BUF, nxt = BUF - cur;
;         const int tn = t + 1 < NT ? t + 1 : t;
;         ka = GLD(u32x4, Kg + (size_t)tn * 768 + kc0); kb = GLD(u32x4, Kg + (size_t)tn * 768 + kc1); va = GLD(u32x4, Vg + (size_t)tn * 512 + tid);
;         u32x4 pf[4];
;         {
;             f32x16 p0 = {}, p1 = {};
; #pragma unroll
;             for (int s = 0; s < 6; ++s) {
;                 const bf16x8 a0 = *(const LAS bf16x8*)(lds + cur + kfo + s * 32), a1 = *(const LAS bf16x8*)(lds + cur + kfo + 32 * KPITCH + s * 32);
;                 const bf16x8 q = *(const LAS bf16x8*)(ql + s * 1024);
;                 p0 = __builtin_amdgcn_mfma_f32_32x32x16_bf16(a0, q, p0, 0, 0, 0); p1 = __builtin_amdgcn_mfma_f32_32x32x16_bf16(a1, q, p1, 0, 0, 0);
;             }
;             softmax_blk(p0, p1, oa0, oa1, ma, la, pf, t == 0);
;             pv_blk(pf, oa0, oa1, lds + cur + vb);
;         }
;         __builtin_amdgcn_sched_barrier(0);
;         {
;             f32x16 p0 = {}, p1 = {};
; #pragma unroll
;             for (int s = 0; s < 6; ++s) {
;                 const bf16x8 a0 = *(const LAS bf16x8*)(lds + cur + kfo + s * 32), a1 = *(const LAS bf16x8*)(lds + cur + kfo + 32 * KPITCH + s * 32);
;                 const bf16x8 q = *(const LAS bf16x8*)(ql + (6 + s) * 1024);
;                 p0 = __builtin_amdgcn_mfma_f32_32x32x16_bf16(a0, q, p0, 0, 0, 0); p1 = __builtin_amdgcn_mfma_f32_32x32x16_bf16(a1, q, p1, 0, 0, 0);
;             }
;             softmax_blk(p0, p1, ob0, ob1, mb, lb, pf, t == 0);
;             pv_blk(pf, ob0, ob1, lds + cur + vb);
;         }
;         *(LAS u32x4*)(lds + nxt + kd0) = ka; *(LAS u32x4*)(lds + (has1 ? nxt : 0u) + kd1) = kb; *(LAS u32x4*)(lds + nxt + vd) = va;
;         __syncthreads();
	v_mfma_f32_32x32x16_bf16 v[96:111], v[176:179], v[186:189], v[96:111]
	v_mfma_f32_32x32x16_bf16 v[112:127], v[180:183], v[186:189], v[112:127]
	ds_read_b128 v[176:179], v155 offset:21664
	ds_read_b128 v[180:183], v155 offset:28320
	ds_read_b128 v[186:189], v135 offset:54272
	v_add_f32_e32 v166, v166, v81
	v_add_f32_e32 v140, v140, v82
	v_add_f32_e32 v166, v166, v83
	v_cvt_pk_bf16_f32 v72, v80, v81
	v_cvt_pk_bf16_f32 v73, v82, v83
	v_exp_f32_e32 v88, v88
	v_exp_f32_e32 v89, v89
	v_exp_f32_e32 v90, v90
	v_exp_f32_e32 v91, v91
	v_add_f32_e32 v140, v140, v84
	s_waitcnt vmcnt(0)
	ds_write_b128 v150, v[218:221]
	ds_write_b128 v156, v[222:225]
	ds_write_b128 v157, v[226:229] offset:34816
	s_waitcnt lgkmcnt(6)
	v_mfma_f32_32x32x16_bf16 v[96:111], v[128:131], v[162:165], v[96:111]
	v_mfma_f32_32x32x16_bf16 v[112:127], v[142:145], v[162:165], v[112:127]
	v_add_f32_e32 v166, v166, v85
	v_add_f32_e32 v140, v140, v86
	v_add_f32_e32 v166, v166, v87
	v_cvt_pk_bf16_f32 v74, v84, v85
	v_cvt_pk_bf16_f32 v75, v86, v87
	v_exp_f32_e32 v92, v92
	v_exp_f32_e32 v93, v93
	v_exp_f32_e32 v94, v94
	v_exp_f32_e32 v95, v95
	s_waitcnt lgkmcnt(3)
	v_mfma_f32_32x32x16_bf16 v[96:111], v[176:179], v[186:189], v[96:111]
	v_mfma_f32_32x32x16_bf16 v[112:127], v[180:183], v[186:189], v[112:127]
	v_add_f32_e32 v140, v140, v88
	v_add_f32_e32 v166, v166, v89
	v_add_f32_e32 v140, v140, v90
	v_add_f32_e32 v166, v166, v91
	v_cvt_pk_bf16_f32 v76, v88, v89
	v_cvt_pk_bf16_f32 v77, v90, v91
	v_add_f32_e32 v140, v140, v92
	v_add_f32_e32 v166, v166, v93
	v_add_f32_e32 v140, v140, v94
	v_add_f32_e32 v166, v166, v95
	v_cvt_pk_bf16_f32 v78, v92, v93
	v_cvt_pk_bf16_f32 v79, v94, v95
	v_add_f32_e32 v140, v140, v166
	s_waitcnt lgkmcnt(0)
	s_barrier
	s_add_i32 s1, s1, 1
	s_cmp_lg_u32 s1, s18
	s_cbranch_scc0 .Lmla_epi
	ds_read_b64_tr_b16 v[128:129], v158 offset:34816
	ds_read_b64_tr_b16 v[130:131], v158 offset:35328
	ds_read_b64_tr_b16 v[142:143], v158 offset:38912
	ds_read_b64_tr_b16 v[144:145], v158 offset:39424
	ds_read_b64_tr_b16 v[176:177], v158 offset:35840
	ds_read_b64_tr_b16 v[178:179], v158 offset:36352
	ds_read_b64_tr_b16 v[180:181], v158 offset:39936
	ds_read_b64_tr_b16 v[182:183], v158 offset:40448
	s_waitcnt lgkmcnt(4)
	v_mfma_f32_32x32x16_bf16 v[16:31], v[128:131], v[64:67], v[16:31]
	v_mfma_f32_32x32x16_bf16 v[0:15], v[142:145], v[64:67], v[0:15]
	ds_read_b64_tr_b16 v[128:129], v158 offset:36864
	ds_read_b64_tr_b16 v[130:131], v158 offset:37376
	ds_read_b64_tr_b16 v[142:143], v158 offset:40960
	ds_read_b64_tr_b16 v[144:145], v158 offset:41472
	v_max3_f32 v248, v96, v97, v98
	v_max3_f32 v249, v112, v113, v114
	v_max3_f32 v248, v248, v99, v100
	v_max3_f32 v249, v249, v115, v116
	v_max3_f32 v248, v248, v101, v102
	v_max3_f32 v249, v249, v117, v118
	v_max3_f32 v248, v248, v103, v104
	v_max3_f32 v249, v249, v119, v120
	v_max3_f32 v248, v248, v105, v106
	v_max3_f32 v249, v249, v121, v122
	v_max3_f32 v248, v248, v107, v108
	v_max3_f32 v249, v249, v123, v124
	v_max3_f32 v248, v248, v109, v110
	v_max3_f32 v249, v249, v125, v126
	s_waitcnt lgkmcnt(4)
	v_mfma_f32_32x32x16_bf16 v[16:31], v[176:179], v[68:71], v[16:31]
	v_mfma_f32_32x32x16_bf16 v[0:15], v[180:183], v[68:71], v[0:15]
	ds_read_b64_tr_b16 v[176:177], v158 offset:37888
	ds_read_b64_tr_b16 v[178:179], v158 offset:38400
	ds_read_b64_tr_b16 v[180:181], v158 offset:41984
	ds_read_b64_tr_b16 v[182:183], v158 offset:42496
	global_load_dwordx4 v[218:221], v171, s[26:27]
	v_max3_f32 v248, v248, v111, v127
	v_max_f32_e32 v248, v248, v249
	v_mov_b32_e32 v251, v248
	s_nop 1
	v_permlane32_swap_b32_e32 v248, v251
	v_max_f32_e32 v167, v248, v251
	v_cmp_lt_f32_e32 vcc, s72, v167
	s_cbranch_vccnz .Lmla_rescBv
.Lmla_rescBv_back:
	v_exp_f32_e32 v96, v96
	v_exp_f32_e32 v97, v97
	v_exp_f32_e32 v98, v98
	s_waitcnt lgkmcnt(4)
	v_mfma_f32_32x32x16_bf16 v[16:31], v[128:131], v[72:75], v[16:31]
	v_mfma_f32_32x32x16_bf16 v[0:15], v[142:145], v[72:75], v[0:15]
	ds_read_b128 v[128:131], v155
	ds_read_b128 v[142:145], v155 offset:6656
	ds_read_b128 v[162:165], v135 offset:43008
	v_exp_f32_e32 v99, v99
	v_exp_f32_e32 v100, v100
	v_exp_f32_e32 v101, v101
	v_exp_f32_e32 v102, v102
	v_exp_f32_e32 v103, v103
	v_add_f32_e32 v166, v96, v97
	v_add_f32_e32 v141, v141, v98
	v_add_f32_e32 v166, v166, v99
	s_waitcnt lgkmcnt(3)
	v_mfma_f32_32x32x16_bf16 v[16:31], v[176:179], v[76:79], v[16:31]
	v_mfma_f32_32x32x16_bf16 v[0:15], v[180:183], v[76:79], v[0:15]
	ds_read_b128 v[176:179], v155 offset:32
	ds_read_b128 v[180:183], v155 offset:6688
	ds_read_b128 v[186:189], v135 offset:44032
	s_cmp_eq_u64 s[36:37], 0
	s_cbranch_scc1 .Lmla_nok1Ae
	global_load_dwordx4 v[222:225], v184, s[26:27]
; #define LAS __attribute__((address_space(3)))
; __device__ __forceinline__ void softmax_blk(f32x16& p0, f32x16& p1, f32x16& o0, f32x16& o1, float& mhat, float& lrun, u32x4 (&pf)[4], bool first) {
;     float r0 = max2_(p0[0], p0[1]), r1 = max2_(p1[0], p1[1]);
; #pragma unroll
;     for (int e = 2; e < 16; ++e) { r0 = max2_(r0, p0[e]); r1 = max2_(r1, p1[e]); }
;     const float rm = swap_max(max2_(r0, r1));
;     if (first || __any(rm - mhat > THR)) {
;         const float mn = first ? rm : fmaxf(rm, mhat); const float f = first ? 0.f : __builtin_amdgcn_exp2f(mhat - mn); mhat = mn; lrun *= f;
; #pragma unroll
;         for (int e = 0; e < 16; ++e) { o0[e] *= f; o1[e] *= f; }
;     }
;     float s0 = 0.f, s1 = 0.f;
; #pragma unroll
;     for (int e = 0; e < 16; ++e) { p0[e] = __builtin_amdgcn_exp2f(p0[e] - mhat); p1[e] = __builtin_amdgcn_exp2f(p1[e] - mhat); s0 += p0[e]; s1 += p1[e]; }
;     lrun += s0 + s1;
;     pf[0] = MLA_PACK(p0, 0); pf[1] = MLA_PACK(p0, 8); pf[2] = MLA_PACK(p1, 0); pf[3] = MLA_PACK(p1, 8);
; }
; __device__ __forceinline__ void pv_blk(const u32x4 (&pf)[4], f32x16& o0, f32x16& o1, LAS const unsigned char* vbase) {
; #pragma unroll
;     for (int ks = 0; ks < 4; ++ks) {
;         const bf16x8 p = __builtin_bit_cast(bf16x8, pf[ks]);
;         { const s16x4 lo = vtr(vbase + ks * 1024), hh = vtr(vbase + ks * 1024 + 512); const bf16x8 vf = {lo[0], lo[1], lo[2], lo[3], hh[0], hh[1], hh[2], hh[3]};
;           o0 = __builtin_amdgcn_mfma_f32_32x32x16_bf16(vf, p, o0, 0, 0, 0); }
;         { const s16x4 lo = vtr(vbase + 4096 + ks * 1024), hh = vtr(vbase + 4096 + ks * 1024 + 512); const bf16x8 vf = {lo[0], lo[1], lo[2], lo[3], hh[0], hh[1], hh[2], hh[3]};
;           o1 = __builtin_amdgcn_mfma_f32_32x32x16_bf16(vf, p, o1, 0, 0, 0); }
;     }
; }
; __device__ __forceinline__ void attn_unit(const bf16_t* Qh, const bf16_t* Kh, const bf16_t* Vh, bf16_t* Oh  , int S, int qb, LAS unsigned char* lds, int tid) {
;     ...
;         ka = GLD(u32x4, Kg + (size_t)tn * 768 + kc0); kb = GLD(u32x4, Kg + (size_t)tn * 768 + kc1); va = GLD(u32x4, Vg + (size_t)tn * 512 + tid);
;         u32x4 pf[4];
;         {
;             f32x16 p0 = {}, p1 = {};
; #pragma unroll
;             for (int s = 0; s < 6; ++s) {
;                 const bf16x8 a0 = *(const LAS bf16x8*)(lds + cur + kfo + s * 32), a1 = *(const LAS bf16x8*)(lds + cur + kfo + 32 * KPITCH + s * 32);
.Lmla_nok1Ae:
	v_cvt_pk_bf16_f32 v96, v96, v97
	v_cvt_pk_bf16_f32 v97, v98, v99
	v_exp_f32_e32 v104, v104
	v_exp_f32_e32 v105, v105
	v_exp_f32_e32 v106, v106
	v_exp_f32_e32 v107, v107
	v_add_f32_e32 v141, v141, v100
	v_add_f32_e32 v166, v166, v101
	v_add_f32_e32 v141, v141, v102
	s_waitcnt lgkmcnt(3)
	v_mfma_f32_32x32x16_bf16 v[64:79], v[128:131], v[162:165], v[232:247]
	v_mfma_f32_32x32x16_bf16 v[80:95], v[142:145], v[162:165], v[232:247]
	ds_read_b128 v[128:131], v155 offset:64
	ds_read_b128 v[142:145], v155 offset:6720
	ds_read_b128 v[162:165], v135 offset:45056
	v_add_f32_e32 v166, v166, v103
	v_cvt_pk_bf16_f32 v98, v100, v101
	v_cvt_pk_bf16_f32 v99, v102, v103
	v_exp_f32_e32 v108, v108
	v_exp_f32_e32 v109, v109
	v_exp_f32_e32 v110, v110
	v_exp_f32_e32 v111, v111
	v_add_f32_e32 v141, v141, v104
	v_add_f32_e32 v166, v166, v105
	s_waitcnt lgkmcnt(3)
	v_mfma_f32_32x32x16_bf16 v[64:79], v[176:179], v[186:189], v[64:79]
	v_mfma_f32_32x32x16_bf16 v[80:95], v[180:183], v[186:189], v[80:95]
	ds_read_b128 v[176:179], v155 offset:96
	ds_read_b128 v[180:183], v155 offset:6752
	ds_read_b128 v[186:189], v135 offset:46080
	global_load_dwordx4 v[226:229], v146, s[100:101]
	s_add_u32 s26, s26, 0x3000
	s_addc_u32 s27, s27, 0
	s_add_u32 s100, s100, 0x2000
	s_addc_u32 s101, s101, 0
	v_add_f32_e32 v141, v141, v106
	v_add_f32_e32 v166, v166, v107
	v_cvt_pk_bf16_f32 v100, v104, v105
	v_cvt_pk_bf16_f32 v101, v106, v107
	v_exp_f32_e32 v112, v112
	v_exp_f32_e32 v113, v113
	v_exp_f32_e32 v114, v114
	v_exp_f32_e32 v115, v115
	v_add_f32_e32 v141, v141, v108
	v_add_f32_e32 v166, v166, v109
	s_waitcnt lgkmcnt(3)
	v_mfma_f32_32x32x16_bf16 v[64:79], v[128:131], v[162:165], v[64:79]
	v_mfma_f32_32x32x16_bf16 v[80:95], v[142:145], v[162:165], v[80:95]
	ds_read_b128 v[128:131], v155 offset:128
	ds_read_b128 v[142:145], v155 offset:6784
	ds_read_b128 v[162:165], v135 offset:47104
	v_add_f32_e32 v141, v141, v110
	v_add_f32_e32 v166, v166, v111
	v_cvt_pk_bf16_f32 v102, v108, v109
	v_cvt_pk_bf16_f32 v103, v110, v111
	v_exp_f32_e32 v116, v116
	v_exp_f32_e32 v117, v117
	v_exp_f32_e32 v118, v118
	v_exp_f32_e32 v119, v119
	v_add_f32_e32 v141, v141, v112
	s_waitcnt lgkmcnt(3)
	v_mfma_f32_32x32x16_bf16 v[64:79], v[176:179], v[186:189], v[64:79]
	v_mfma_f32_32x32x16_bf16 v[80:95], v[180:183], v[186:189], v[80:95]
	ds_read_b128 v[176:179], v155 offset:160
	ds_read_b128 v[180:183], v155 offset:6816
	ds_read_b128 v[186:189], v135 offset:48128
	v_add_f32_e32 v166, v166, v113
	v_add_f32_e32 v141, v141, v114
	v_add_f32_e32 v166, v166, v115
	v_cvt_pk_bf16_f32 v104, v112, v113
	v_cvt_pk_bf16_f32 v105, v114, v115
	v_exp_f32_e32 v120, v120
	v_exp_f32_e32 v121, v121
	v_exp_f32_e32 v122, v122
	v_exp_f32_e32 v123, v123
	v_add_f32_e32 v141, v141, v116
	s_waitcnt lgkmcnt(3)
	v_mfma_f32_32x32x16_bf16 v[64:79], v[128:131], v[162:165], v[64:79]
	v_mfma_f32_32x32x16_bf16 v[80:95], v[142:145], v[162:165], v[80:95]
	ds_read_b64_tr_b16 v[128:129], v158 offset:34816
	ds_read_b64_tr_b16 v[130:131], v158 offset:35328
	ds_read_b64_tr_b16 v[142:143], v158 offset:38912
	ds_read_b64_tr_b16 v[144:145], v158 offset:39424
	v_add_f32_e32 v166, v166, v117
	v_add_f32_e32 v141, v141, v118
	v_add_f32_e32 v166, v166, v119
	v_cvt_pk_bf16_f32 v106, v116, v117
	v_cvt_pk_bf16_f32 v107, v118, v119
	v_exp_f32_e32 v124, v124
	v_exp_f32_e32 v125, v125
	v_exp_f32_e32 v126, v126
	v_exp_f32_e32 v127, v127
	s_waitcnt lgkmcnt(4)
	v_mfma_f32_32x32x16_bf16 v[64:79], v[176:179], v[186:189], v[64:79]
	v_mfma_f32_32x32x16_bf16 v[80:95], v[180:183], v[186:189], v[80:95]
	ds_read_b64_tr_b16 v[176:177], v158 offset:35840
	ds_read_b64_tr_b16 v[178:179], v158 offset:36352
	ds_read_b64_tr_b16 v[180:181], v158 offset:39936
	ds_read_b64_tr_b16 v[182:183], v158 offset:40448
	v_add_f32_e32 v141, v141, v120
	v_add_f32_e32 v166, v166, v121
	v_add_f32_e32 v141, v141, v122
	v_add_f32_e32 v166, v166, v123
	v_cvt_pk_bf16_f32 v108, v120, v121
	v_cvt_pk_bf16_f32 v109, v122, v123
	v_add_f32_e32 v141, v141, v124
	v_add_f32_e32 v166, v166, v125
	v_add_f32_e32 v141, v141, v126
	v_add_f32_e32 v166, v166, v127
	v_cvt_pk_bf16_f32 v110, v124, v125
	v_cvt_pk_bf16_f32 v111, v126, v127
	v_add_f32_e32 v141, v141, v166
	s_waitcnt lgkmcnt(4)
	v_mfma_f32_32x32x16_bf16 v[48:63], v[128:131], v[96:99], v[48:63]
	v_mfma_f32_32x32x16_bf16 v[32:47], v[142:145], v[96:99], v[32:47]
	ds_read_b64_tr_b16 v[128:129], v158 offset:36864
	ds_read_b64_tr_b16 v[130:131], v158 offset:37376
	ds_read_b64_tr_b16 v[142:143], v158 offset:40960
	ds_read_b64_tr_b16 v[144:145], v158 offset:41472
	v_max3_f32 v248, v64, v65, v66
	v_max3_f32 v249, v80, v81, v82
	v_max3_f32 v248, v248, v67, v68
	v_max3_f32 v249, v249, v83, v84
	v_max3_f32 v248, v248, v69, v70
	v_max3_f32 v249, v249, v85, v86
	v_max3_f32 v248, v248, v71, v72
	v_max3_f32 v249, v249, v87, v88
	v_max3_f32 v248, v248, v73, v74
	v_max3_f32 v249, v249, v89, v90
	v_max3_f32 v248, v248, v75, v76
	v_max3_f32 v249, v249, v91, v92
	v_max3_f32 v248, v248, v77, v78
	v_max3_f32 v249, v249, v93, v94
	s_waitcnt lgkmcnt(4)
	v_mfma_f32_32x32x16_bf16 v[48:63], v[176:179], v[100:103], v[48:63]
	v_mfma_f32_32x32x16_bf16 v[32:47], v[180:183], v[100:103], v[32:47]
	ds_read_b64_tr_b16 v[176:177], v158 offset:37888
	ds_read_b64_tr_b16 v[178:179], v158 offset:38400
	ds_read_b64_tr_b16 v[180:181], v158 offset:41984
	ds_read_b64_tr_b16 v[182:183], v158 offset:42496
	v_max3_f32 v248, v248, v79, v95
	v_max_f32_e32 v248, v248, v249
	v_mov_b32_e32 v251, v248
	s_nop 1
	v_permlane32_swap_b32_e32 v248, v251
	v_max_f32_e32 v167, v248, v251
	v_cmp_lt_f32_e32 vcc, s72, v167
	s_cbranch_vccnz .Lmla_rescAe
